# merge phase: per-workgroup rotation of branch order and K-tile order (spreads L2 channel load)
# speedup vs baseline: 1.0073x; 1.0073x over previous
.LBB0_277:
	s_andn2_b64 vcc, exec, s[0:1]
	s_cbranch_vccnz .LBB0_284
	v_readlane_b32 s20, v253, 13
	v_readlane_b32 s21, v253, 14
	v_readlane_b32 s34, v252, 0
	v_readlane_b32 s99, v254, 62
	s_load_dword s16, s[20:21], 0x0
	s_sub_u32 s20, s20, 0x218
	s_subb_u32 s21, s21, 0
	s_load_dwordx2 s[2:3], s[20:21], 0x138
	s_load_dwordx2 s[8:9], s[20:21], 0x150
	s_load_dwordx2 s[6:7], s[20:21], 0x158
	s_load_dwordx2 s[0:1], s[20:21], 0x160
	v_lshrrev_b32_e32 v0, 3, v194
	v_lshrrev_b32_e32 v1, 4, v194
	v_xor_b32_e32 v1, v1, v194
	v_and_b32_e32 v1, 7, v1
	v_lshlrev_b32_e32 v1, 4, v1
	v_add_u32_e32 v3, 0, v0
	v_lshl_or_b32 v132, v3, 12, v1
	v_lshl_or_b32 v222, v3, 10, v1
	v_add_u32_e32 v3, 32, v0
	v_lshl_or_b32 v133, v3, 12, v1
	v_lshl_or_b32 v223, v3, 10, v1
	v_add_u32_e32 v3, 64, v0
	v_lshl_or_b32 v134, v3, 12, v1
	v_lshl_or_b32 v224, v3, 10, v1
	v_add_u32_e32 v3, 96, v0
	v_lshl_or_b32 v135, v3, 12, v1
	v_lshl_or_b32 v225, v3, 10, v1
	v_and_b32_e32 v0, 15, v194
	v_lshrrev_b32_e32 v1, 1, v0
	v_bfe_u32 v3, v194, 4, 2
	v_xor_b32_e32 v1, v1, v3
	v_lshlrev_b32_e32 v1, 4, v1
	v_lshl_or_b32 v1, v0, 7, v1
	v_lshrrev_b32_e32 v3, 7, v194
	v_lshl_or_b32 v226, v3, 13, v1
	v_bfe_u32 v3, v194, 6, 1
	v_lshl_or_b32 v3, v3, 13, v1
	v_or_b32_e32 v228, 0x4000, v3
	v_xor_b32_e32 v227, 64, v226
	v_xor_b32_e32 v229, 64, v228
	v_lshrrev_b32_e32 v1, 7, v194
	v_lshl_or_b32 v0, v1, 6, v0
	v_bfe_u32 v1, v194, 6, 1
	v_lshlrev_b32_e32 v1, 6, v1
	v_bfe_u32 v3, v194, 4, 2
	v_lshl_or_b32 v1, v3, 2, v1
	v_lshlrev_b32_e32 v1, 1, v1
	v_add_u32_e32 v3, 0, v0
	v_lshl_or_b32 v230, v3, 13, v1
	v_lshl_or_b32 v234, v3, 11, v1
	v_add_u32_e32 v3, 16, v0
	v_lshl_or_b32 v231, v3, 13, v1
	v_lshl_or_b32 v235, v3, 11, v1
	v_add_u32_e32 v3, 32, v0
	v_lshl_or_b32 v232, v3, 13, v1
	v_lshl_or_b32 v236, v3, 11, v1
	v_add_u32_e32 v3, 48, v0
	v_lshl_or_b32 v233, v3, 13, v1
	v_lshl_or_b32 v237, v3, 11, v1
	v_lshrrev_b32_e32 v0, 6, v194
	v_lshlrev_b32_e32 v0, 10, v0
	s_nop 0
	v_readfirstlane_b32 s100, v0
	v_mov_b64_e32 v[4:5], 0
	v_mov_b64_e32 v[6:7], 0
	v_mov_b64_e32 v[8:9], 0
	v_mov_b64_e32 v[10:11], 0
	v_mov_b64_e32 v[12:13], 0
	v_mov_b64_e32 v[14:15], 0
	v_mov_b64_e32 v[16:17], 0
	v_mov_b64_e32 v[18:19], 0
	v_mov_b64_e32 v[20:21], 0
	v_mov_b64_e32 v[22:23], 0
	v_mov_b64_e32 v[24:25], 0
	v_mov_b64_e32 v[26:27], 0
	v_mov_b64_e32 v[28:29], 0
	v_mov_b64_e32 v[30:31], 0
	v_mov_b64_e32 v[32:33], 0
	v_mov_b64_e32 v[34:35], 0
	v_mov_b64_e32 v[36:37], 0
	v_mov_b64_e32 v[38:39], 0
	v_mov_b64_e32 v[40:41], 0
	v_mov_b64_e32 v[42:43], 0
	v_mov_b64_e32 v[44:45], 0
	v_mov_b64_e32 v[46:47], 0
	v_mov_b64_e32 v[48:49], 0
	v_mov_b64_e32 v[50:51], 0
	v_mov_b64_e32 v[52:53], 0
	v_mov_b64_e32 v[54:55], 0
	v_mov_b64_e32 v[56:57], 0
	v_mov_b64_e32 v[58:59], 0
	v_mov_b64_e32 v[60:61], 0
	v_mov_b64_e32 v[62:63], 0
	v_mov_b64_e32 v[64:65], 0
	v_mov_b64_e32 v[66:67], 0
	v_mov_b64_e32 v[68:69], 0
	v_mov_b64_e32 v[70:71], 0
	v_mov_b64_e32 v[72:73], 0
	v_mov_b64_e32 v[74:75], 0
	v_mov_b64_e32 v[76:77], 0
	v_mov_b64_e32 v[78:79], 0
	v_mov_b64_e32 v[80:81], 0
	v_mov_b64_e32 v[82:83], 0
	v_mov_b64_e32 v[84:85], 0
	v_mov_b64_e32 v[86:87], 0
	v_mov_b64_e32 v[88:89], 0
	v_mov_b64_e32 v[90:91], 0
	v_mov_b64_e32 v[92:93], 0
	v_mov_b64_e32 v[94:95], 0
	v_mov_b64_e32 v[96:97], 0
	v_mov_b64_e32 v[98:99], 0
	v_mov_b64_e32 v[100:101], 0
	v_mov_b64_e32 v[102:103], 0
	v_mov_b64_e32 v[104:105], 0
	v_mov_b64_e32 v[106:107], 0
	v_mov_b64_e32 v[108:109], 0
	v_mov_b64_e32 v[110:111], 0
	v_mov_b64_e32 v[112:113], 0
	v_mov_b64_e32 v[114:115], 0
	v_mov_b64_e32 v[116:117], 0
	v_mov_b64_e32 v[118:119], 0
	v_mov_b64_e32 v[120:121], 0
	v_mov_b64_e32 v[122:123], 0
	v_mov_b64_e32 v[124:125], 0
	v_mov_b64_e32 v[126:127], 0
	v_mov_b64_e32 v[128:129], 0
	v_mov_b64_e32 v[130:131], 0
	s_waitcnt lgkmcnt(0)
	s_cmp_gt_i32 s99, 9
	s_cselect_b32 s99, 0x400000, 0
	s_add_u32 s2, s2, s99
	s_addc_u32 s3, s3, 0
	s_lshr_b32 s16, s16, 3
	s_mov_b32 s15, 0
	s_and_b32 s99, s34, 7
	s_lshl_b32 vcc_lo, s15, 3
	s_add_u32 s99, s99, vcc_lo
	s_mul_i32 s99, s99, s16
	s_lshr_b32 vcc_lo, s34, 3
	s_add_u32 s99, s99, vcc_lo
	s_cmp_lt_u32 s99, 0x440
	s_cselect_b32 s17, 1, 0
	s_lshr_b32 vcc_lo, s99, 6
	s_lshl_b32 vcc_lo, vcc_lo, 3
	s_and_b32 vcc_hi, s99, 7
	s_add_u32 vcc_lo, vcc_lo, vcc_hi
	s_lshl_b32 s10, vcc_lo, 7
	s_bfe_u32 vcc_lo, s99, 0x30003
	s_lshl_b32 s11, vcc_lo, 7
	s_cmp_eq_u32 s17, 0
	s_cbranch_scc1 .Lmg_exit
	s_mov_b32 s15, 1
	s_and_b32 s99, s34, 7
	s_lshl_b32 vcc_lo, s15, 3
	s_add_u32 s99, s99, vcc_lo
	s_mul_i32 s99, s99, s16
	s_lshr_b32 vcc_lo, s34, 3
	s_add_u32 s99, s99, vcc_lo
	s_cmp_lt_u32 s99, 0x440
	s_cselect_b32 s17, 1, 0
	s_lshr_b32 vcc_lo, s99, 6
	s_lshl_b32 vcc_lo, vcc_lo, 3
	s_and_b32 vcc_hi, s99, 7
	s_add_u32 vcc_lo, vcc_lo, vcc_hi
	s_lshl_b32 s12, vcc_lo, 7
	s_bfe_u32 vcc_lo, s99, 0x30003
	s_lshl_b32 s13, vcc_lo, 7
	s_mov_b32 s14, 0
	s_bfe_u32 m0, s34, 0x20003
	s_add_u32 m0, m0, s14
	s_and_b32 m0, m0, 3
	s_lshl_b32 vcc_lo, s10, 12
	s_lshl_b32 vcc_hi, m0, 10
	s_add_u32 vcc_lo, vcc_lo, vcc_hi
	s_add_u32 s18, s0, vcc_lo
	s_addc_u32 s19, s1, 0
	s_lshl_b32 vcc_lo, s11, 10
	s_lshl_b32 vcc_hi, m0, 20
	s_add_u32 vcc_lo, vcc_lo, vcc_hi
	s_add_u32 s20, s2, vcc_lo
	s_addc_u32 s21, s3, 0
	s_bfe_u32 m0, s34, 0x20003
	s_add_u32 m0, m0, s14
	s_and_b32 m0, m0, 3
	s_lshl_b32 vcc_lo, s10, 13
	s_lshl_b32 vcc_hi, m0, 11
	s_add_u32 vcc_lo, vcc_lo, vcc_hi
	s_lshl_b32 vcc_hi, s11, 1
	s_add_u32 vcc_lo, vcc_lo, vcc_hi
	s_add_u32 s38, s6, vcc_lo
	s_addc_u32 s39, s7, 0
	s_lshl_b32 vcc_lo, s10, 11
	s_lshl_b32 vcc_hi, s11, 1
	s_add_u32 vcc_lo, vcc_lo, vcc_hi
	s_add_u32 s40, s8, vcc_lo
	s_addc_u32 s41, s9, 0
	s_cmp_lt_u32 s14, 3
	s_cbranch_scc0 .Lmg_nt_0
	s_add_u32 s99, s14, 1
	s_bfe_u32 m0, s34, 0x20003
	s_add_u32 m0, m0, s99
	s_and_b32 m0, m0, 3
	s_lshl_b32 vcc_lo, s10, 12
	s_lshl_b32 vcc_hi, m0, 10
	s_add_u32 vcc_lo, vcc_lo, vcc_hi
	s_add_u32 s22, s0, vcc_lo
	s_addc_u32 s23, s1, 0
	s_lshl_b32 vcc_lo, s11, 10
	s_lshl_b32 vcc_hi, m0, 20
	s_add_u32 vcc_lo, vcc_lo, vcc_hi
	s_add_u32 s24, s2, vcc_lo
	s_addc_u32 s25, s3, 0
	s_mov_b32 s35, 1
	s_branch .Lmg_nd_0
.Lmg_nt_0:
	s_mov_b32 s99, 0
	s_bfe_u32 m0, s34, 0x20003
	s_add_u32 m0, m0, s99
	s_and_b32 m0, m0, 3
	s_lshl_b32 vcc_lo, s12, 12
	s_lshl_b32 vcc_hi, m0, 10
	s_add_u32 vcc_lo, vcc_lo, vcc_hi
	s_add_u32 s22, s0, vcc_lo
	s_addc_u32 s23, s1, 0
	s_lshl_b32 vcc_lo, s13, 10
	s_lshl_b32 vcc_hi, m0, 20
	s_add_u32 vcc_lo, vcc_lo, vcc_hi
	s_add_u32 s24, s2, vcc_lo
	s_addc_u32 s25, s3, 0
	s_mov_b32 s35, s17
.Lmg_nd_0:
	s_mov_b32 vcc_lo, 0
	s_bfe_u32 vcc_hi, s34, 0x30005
	s_add_u32 vcc_lo, vcc_lo, vcc_hi
	s_and_b32 vcc_lo, vcc_lo, 7
	s_lshl_b32 vcc_lo, vcc_lo, 7
	s_add_u32 s26, s18, vcc_lo
	s_addc_u32 s27, s19, 0
	s_add_u32 s30, s20, vcc_lo
	s_addc_u32 s31, s21, 0
	s_add_u32 m0, s100, 0x0
	s_nop 0
	global_load_lds_dwordx4 v132, s[26:27]
	s_add_u32 m0, s100, 0x1000
	s_nop 0
	global_load_lds_dwordx4 v133, s[26:27]
	s_add_u32 m0, s100, 0x2000
	s_nop 0
	global_load_lds_dwordx4 v134, s[26:27]
	s_add_u32 m0, s100, 0x3000
	s_nop 0
	global_load_lds_dwordx4 v135, s[26:27]
	s_add_u32 m0, s100, 0x4000
	s_nop 0
	global_load_lds_dwordx4 v222, s[30:31]
	s_add_u32 m0, s100, 0x5000
	s_nop 0
	global_load_lds_dwordx4 v223, s[30:31]
	s_add_u32 m0, s100, 0x6000
	s_nop 0
	global_load_lds_dwordx4 v224, s[30:31]
	s_add_u32 m0, s100, 0x7000
	s_nop 0
	global_load_lds_dwordx4 v225, s[30:31]
	s_waitcnt vmcnt(0)
	s_barrier

.Lmg_body0:
	s_sub_u32 s99, s98, 1
	s_mov_b32 vcc_lo, s99
	s_bfe_u32 vcc_hi, s34, 0x30005
	s_add_u32 vcc_lo, vcc_lo, vcc_hi
	s_and_b32 vcc_lo, vcc_lo, 7
	s_lshl_b32 vcc_lo, vcc_lo, 7
	s_add_u32 s26, s18, vcc_lo
	s_addc_u32 s27, s19, 0
	s_add_u32 s30, s20, vcc_lo
	s_addc_u32 s31, s21, 0
	s_add_u32 m0, s100, 0x8000
	s_nop 0
	global_load_lds_dwordx4 v132, s[26:27]
	s_add_u32 m0, s100, 0x9000
	s_nop 0
	global_load_lds_dwordx4 v133, s[26:27]
	s_add_u32 m0, s100, 0xa000
	s_nop 0
	global_load_lds_dwordx4 v134, s[26:27]
	s_add_u32 m0, s100, 0xb000
	s_nop 0
	global_load_lds_dwordx4 v135, s[26:27]
	s_waitcnt lgkmcnt(7)
	ds_read_b128 v[172:175], v229
	ds_read_b128 v[176:179], v227
	ds_read_b128 v[180:183], v229 offset:2048
	ds_read_b128 v[184:187], v229 offset:4096
	ds_read_b128 v[188:191], v229 offset:6144
	ds_read_b128 v[208:211], v227 offset:2048
	ds_read_b128 v[214:217], v227 offset:4096
	ds_read_b128 v[218:221], v227 offset:6144
	s_add_u32 m0, s100, 0xc000
	s_waitcnt lgkmcnt(14)
	v_mfma_f32_16x16x32_bf16 v[68:71], v[140:143], v[144:147], v[68:71]
	global_load_lds_dwordx4 v222, s[30:31]
	s_waitcnt lgkmcnt(13)
	v_mfma_f32_16x16x32_bf16 v[72:75], v[148:151], v[144:147], v[72:75]
	s_waitcnt lgkmcnt(12)
	v_mfma_f32_16x16x32_bf16 v[76:79], v[152:155], v[144:147], v[76:79]
	s_waitcnt lgkmcnt(11)
	v_mfma_f32_16x16x32_bf16 v[80:83], v[156:159], v[144:147], v[80:83]
	s_add_u32 m0, s100, 0xd000
	s_waitcnt lgkmcnt(10)
	v_mfma_f32_16x16x32_bf16 v[84:87], v[140:143], v[160:163], v[84:87]
	global_load_lds_dwordx4 v223, s[30:31]
	v_mfma_f32_16x16x32_bf16 v[88:91], v[148:151], v[160:163], v[88:91]
	v_mfma_f32_16x16x32_bf16 v[92:95], v[152:155], v[160:163], v[92:95]
	v_mfma_f32_16x16x32_bf16 v[96:99], v[156:159], v[160:163], v[96:99]
	s_add_u32 m0, s100, 0xe000
	s_waitcnt lgkmcnt(9)
	v_mfma_f32_16x16x32_bf16 v[100:103], v[140:143], v[164:167], v[100:103]
	global_load_lds_dwordx4 v224, s[30:31]
	v_mfma_f32_16x16x32_bf16 v[104:107], v[148:151], v[164:167], v[104:107]
	v_mfma_f32_16x16x32_bf16 v[108:111], v[152:155], v[164:167], v[108:111]
	v_mfma_f32_16x16x32_bf16 v[112:115], v[156:159], v[164:167], v[112:115]
	s_add_u32 m0, s100, 0xf000
	s_waitcnt lgkmcnt(8)
	v_mfma_f32_16x16x32_bf16 v[116:119], v[140:143], v[168:171], v[116:119]
	global_load_lds_dwordx4 v225, s[30:31]
	v_mfma_f32_16x16x32_bf16 v[120:123], v[148:151], v[168:171], v[120:123]
	v_mfma_f32_16x16x32_bf16 v[124:127], v[152:155], v[168:171], v[124:127]
	v_mfma_f32_16x16x32_bf16 v[128:131], v[156:159], v[168:171], v[128:131]
	s_waitcnt lgkmcnt(6)
	v_mfma_f32_16x16x32_bf16 v[68:71], v[172:175], v[176:179], v[68:71]
	s_waitcnt lgkmcnt(5)
	v_mfma_f32_16x16x32_bf16 v[72:75], v[180:183], v[176:179], v[72:75]
	s_waitcnt lgkmcnt(4)
	v_mfma_f32_16x16x32_bf16 v[76:79], v[184:187], v[176:179], v[76:79]
	s_waitcnt lgkmcnt(3)
	v_mfma_f32_16x16x32_bf16 v[80:83], v[188:191], v[176:179], v[80:83]
	s_waitcnt lgkmcnt(2)
	v_mfma_f32_16x16x32_bf16 v[84:87], v[172:175], v[208:211], v[84:87]
	v_mfma_f32_16x16x32_bf16 v[88:91], v[180:183], v[208:211], v[88:91]
	v_mfma_f32_16x16x32_bf16 v[92:95], v[184:187], v[208:211], v[92:95]
	v_mfma_f32_16x16x32_bf16 v[96:99], v[188:191], v[208:211], v[96:99]
	s_cmp_lt_u32 s98, 8
	s_cbranch_scc1 .Lmg_samesub
	s_cmp_eq_u32 s35, 0
	s_cbranch_scc1 .Lmg_cur
	s_mov_b32 vcc_lo, 0
	s_bfe_u32 vcc_hi, s34, 0x30005
	s_add_u32 vcc_lo, vcc_lo, vcc_hi
	s_and_b32 vcc_lo, vcc_lo, 7
	s_lshl_b32 vcc_lo, vcc_lo, 7
	s_add_u32 s26, s22, vcc_lo
	s_addc_u32 s27, s23, 0
	s_add_u32 s30, s24, vcc_lo
	s_addc_u32 s31, s25, 0
	s_branch .Lmg_go
.Lmg_cur:
	s_mov_b32 vcc_lo, 0
	s_bfe_u32 vcc_hi, s34, 0x30005
	s_add_u32 vcc_lo, vcc_lo, vcc_hi
	s_and_b32 vcc_lo, vcc_lo, 7
	s_lshl_b32 vcc_lo, vcc_lo, 7
	s_add_u32 s26, s18, vcc_lo
	s_addc_u32 s27, s19, 0
	s_add_u32 s30, s20, vcc_lo
	s_addc_u32 s31, s21, 0
	s_branch .Lmg_go
.Lmg_samesub:
	s_mov_b32 vcc_lo, s98
	s_bfe_u32 vcc_hi, s34, 0x30005
	s_add_u32 vcc_lo, vcc_lo, vcc_hi
	s_and_b32 vcc_lo, vcc_lo, 7
	s_lshl_b32 vcc_lo, vcc_lo, 7
	s_add_u32 s26, s18, vcc_lo
	s_addc_u32 s27, s19, 0
	s_add_u32 s30, s20, vcc_lo
	s_addc_u32 s31, s21, 0

.Lmg_nogp:
	s_add_u32 m0, s100, 0x0
	s_nop 0
	global_load_lds_dwordx4 v132, s[26:27]
	s_add_u32 m0, s100, 0x1000
	s_nop 0
	global_load_lds_dwordx4 v133, s[26:27]
	s_add_u32 m0, s100, 0x2000
	s_nop 0
	global_load_lds_dwordx4 v134, s[26:27]
	s_add_u32 m0, s100, 0x3000
	s_nop 0
	global_load_lds_dwordx4 v135, s[26:27]
	s_waitcnt lgkmcnt(7)
	ds_read_b128 v[172:175], v229 offset:32768
	ds_read_b128 v[176:179], v227 offset:32768
	ds_read_b128 v[180:183], v229 offset:34816
	ds_read_b128 v[184:187], v229 offset:36864
	ds_read_b128 v[188:191], v229 offset:38912
	ds_read_b128 v[208:211], v227 offset:34816
	ds_read_b128 v[214:217], v227 offset:36864
	ds_read_b128 v[218:221], v227 offset:38912
	s_add_u32 m0, s100, 0x4000
	s_waitcnt lgkmcnt(14)
	v_mfma_f32_16x16x32_bf16 v[68:71], v[140:143], v[144:147], v[68:71]
	global_load_lds_dwordx4 v222, s[30:31]
	s_waitcnt lgkmcnt(13)
	v_mfma_f32_16x16x32_bf16 v[72:75], v[148:151], v[144:147], v[72:75]
	s_waitcnt lgkmcnt(12)
	v_mfma_f32_16x16x32_bf16 v[76:79], v[152:155], v[144:147], v[76:79]
	s_waitcnt lgkmcnt(11)
	v_mfma_f32_16x16x32_bf16 v[80:83], v[156:159], v[144:147], v[80:83]
	s_add_u32 m0, s100, 0x5000
	s_waitcnt lgkmcnt(10)
	v_mfma_f32_16x16x32_bf16 v[84:87], v[140:143], v[160:163], v[84:87]
	global_load_lds_dwordx4 v223, s[30:31]
	v_mfma_f32_16x16x32_bf16 v[88:91], v[148:151], v[160:163], v[88:91]
	v_mfma_f32_16x16x32_bf16 v[92:95], v[152:155], v[160:163], v[92:95]
	v_mfma_f32_16x16x32_bf16 v[96:99], v[156:159], v[160:163], v[96:99]
	s_add_u32 m0, s100, 0x6000
	s_waitcnt lgkmcnt(9)
	v_mfma_f32_16x16x32_bf16 v[100:103], v[140:143], v[164:167], v[100:103]
	global_load_lds_dwordx4 v224, s[30:31]
	v_mfma_f32_16x16x32_bf16 v[104:107], v[148:151], v[164:167], v[104:107]
	v_mfma_f32_16x16x32_bf16 v[108:111], v[152:155], v[164:167], v[108:111]
	v_mfma_f32_16x16x32_bf16 v[112:115], v[156:159], v[164:167], v[112:115]
	s_add_u32 m0, s100, 0x7000
	s_waitcnt lgkmcnt(8)
	v_mfma_f32_16x16x32_bf16 v[116:119], v[140:143], v[168:171], v[116:119]
	global_load_lds_dwordx4 v225, s[30:31]
	v_mfma_f32_16x16x32_bf16 v[120:123], v[148:151], v[168:171], v[120:123]
	v_mfma_f32_16x16x32_bf16 v[124:127], v[152:155], v[168:171], v[124:127]
	v_mfma_f32_16x16x32_bf16 v[128:131], v[156:159], v[168:171], v[128:131]
	s_cmp_lt_u32 s98, 8
	s_cbranch_scc1 .Lmg_nogp2
	global_load_dwordx2 v[140:141], v232, s[38:39] offset:0
	global_load_dwordx2 v[144:145], v232, s[38:39] offset:32
	global_load_dwordx2 v[148:149], v232, s[38:39] offset:64
	global_load_dwordx2 v[152:153], v232, s[38:39] offset:96
	global_load_dwordx2 v[156:157], v233, s[38:39] offset:0
	global_load_dwordx2 v[160:161], v233, s[38:39] offset:32
	global_load_dwordx2 v[164:165], v233, s[38:39] offset:64
	global_load_dwordx2 v[168:169], v233, s[38:39] offset:96

.Lmg_advd:
	s_bfe_u32 m0, s34, 0x20003
	s_add_u32 m0, m0, s14
	s_and_b32 m0, m0, 3
	s_lshl_b32 vcc_lo, s10, 13
	s_lshl_b32 vcc_hi, m0, 11
	s_add_u32 vcc_lo, vcc_lo, vcc_hi
	s_lshl_b32 vcc_hi, s11, 1
	s_add_u32 vcc_lo, vcc_lo, vcc_hi
	s_add_u32 s38, s6, vcc_lo
	s_addc_u32 s39, s7, 0
	s_lshl_b32 vcc_lo, s10, 11
	s_lshl_b32 vcc_hi, s11, 1
	s_add_u32 vcc_lo, vcc_lo, vcc_hi
	s_add_u32 s40, s8, vcc_lo
	s_addc_u32 s41, s9, 0
	s_cmp_lt_u32 s14, 3
	s_cbranch_scc0 .Lmg_nt_1
	s_add_u32 s99, s14, 1
	s_bfe_u32 m0, s34, 0x20003
	s_add_u32 m0, m0, s99
	s_and_b32 m0, m0, 3
	s_lshl_b32 vcc_lo, s10, 12
	s_lshl_b32 vcc_hi, m0, 10
	s_add_u32 vcc_lo, vcc_lo, vcc_hi
	s_add_u32 s22, s0, vcc_lo
	s_addc_u32 s23, s1, 0
	s_lshl_b32 vcc_lo, s11, 10
	s_lshl_b32 vcc_hi, m0, 20
	s_add_u32 vcc_lo, vcc_lo, vcc_hi
	s_add_u32 s24, s2, vcc_lo
	s_addc_u32 s25, s3, 0
	s_mov_b32 s35, 1
	s_branch .Lmg_nd_1
